# row_post work queue: chunks written in the first half of the z GEMM first (LRU-aware oldest-first order)
# speedup vs baseline: 1.0059x; 1.0053x over previous
; #define INP(i) ((const float*)tab_get(lds, (i)))
; #define OUTP() ((float*)tab_get(lds, 30))
; #define WSB(off) ((bf16*)((unsigned char*)tab_get(lds, 31) + (off)))
; #define fresh_lane() (my_tid(lds) & 63)
; #define QNEXT(ctrw, dst) do { __syncthreads(); if (my_tid(lds) == 0) *(volatile LAS int*)(lds + TAB_OFF + 264) = (int)atomicAdd((unsigned*)tab_get(lds, 31) + 8192 + 64 * (ctrw), 1u); \
;         __syncthreads(); dst = __builtin_amdgcn_readfirstlane(*(volatile LAS int*)(lds + TAB_OFF + 264)); } while (0)
; __global__ void __launch_bounds__(512, 2) mega_fwd(Params p) {
;     ...
;         { const int lane = fresh_lane(); bf16 *Z = WSB(WS_Z), *CQN = WSB(WS_CQN), *CKV = WSB(WS_CKV), *KR = WSB(WS_KR); float* out = OUTP(); const float *qg = INP(11), *kvg = INP(12);
;           for (;;) { int it; QNEXT(0, it); if (it >= MP / 64) break;
; #pragma unroll 1
;               for (int k = 0; k < 8; ++k) row_post(Z, CQN, CKV, KR, out, qg, kvg, it * 64 + wave * 8 + k, lane); } }
.LBB0_318:
	s_or_b64 exec, exec, s[8:9]
	s_waitcnt lgkmcnt(0)
	s_barrier
	ds_read_b32 v20, v38
	s_mov_b64 s[8:9], -1
	s_waitcnt lgkmcnt(0)
	v_readfirstlane_b32 s4, v20
	s_cmpk_gt_i32 s4, 0x1ff
	s_cbranch_scc1 .LBB0_315
	s_lshr_b32 s8, s4, 5
	s_and_b32 s9, s4, 31
	s_lshl_b32 s4, s8, 1
	s_or_b32 s4, s4, 1
	s_cmp_lt_u32 s8, 8
	s_cselect_b32 s8, 1, 16
	s_sub_i32 s4, s4, s8
	s_lshl_b32 s4, s4, 5
	s_or_b32 s4, s4, s9
	s_lshl_b32 s4, s4, 6
	s_add_i32 s8, s4, s70
	s_ashr_i32 s9, s8, 31
	s_lshl_b64 s[10:11], s[8:9], 8
	v_lshl_add_u64 v[20:21], v[6:7], 0, s[10:11]
	s_lshl_b64 s[10:11], s[8:9], 6
	v_lshl_add_u64 v[22:23], v[8:9], 0, s[10:11]
	s_lshl_b64 s[10:11], s[8:9], 9
	s_add_u32 s28, s20, s10
	v_lshl_add_u64 v[24:25], v[10:11], 0, s[10:11]
	s_addc_u32 s29, s21, s11
	v_mad_i64_i32 v[26:27], s[10:11], s8, v40, v[12:13]
	v_mad_i64_i32 v[28:29], s[10:11], s8, v40, v[14:15]
	v_mad_i64_i32 v[30:31], s[10:11], s8, v40, v[16:17]
	s_add_i32 s4, s23, s4
	s_and_b32 s30, s8, 0x3fff
	s_lshl_b64 s[10:11], s[4:5], 9
	s_add_u32 s31, s24, s10
	s_addc_u32 s34, s25, s11
	s_mov_b64 s[10:11], 0
	s_mov_b64 s[12:13], 0
	s_mov_b64 s[14:15], 0
	s_branch .LBB0_321
